# v45 = v43 + MT2 k-loops: the eight 64-bit load address computations per staging set replaced by loop-invariant 32-bit offsets with SGPR-base addressing (no address VALU in the loop)
# baseline (speedup 1.0000x reference)
.LBB0_832:
	s_lshl_b32 s6, s57, 11
	s_and_b32 s6, s6, 0x1c0000
	s_add_u32 s10, s30, s6
	s_addc_u32 s11, s31, 0
	s_lshr_b32 s18, s58, 3
	s_lshl_b32 s6, s18, 7
	s_add_i32 s6, s35, s6
	s_lshl_b64 s[8:9], s[6:7], 11
	s_add_u32 s12, s30, s8
	s_addc_u32 s13, s31, s9
	s_lshl_b32 s8, s58, 7
	s_and_b32 s59, s8, 0x380
	s_mov_b64 s[8:9], s[30:31]
	v_mov_b32_e32 v0, v201
	s_add_i32 s18, s18, s25
	v_mbcnt_lo_u32_b32 v0, -1, v0
	v_mbcnt_hi_u32_b32 v0, -1, v0
	s_lshl_b32 s6, s18, 7
	v_add_u32_e32 v202, s33, v0
	s_lshl_b64 s[16:17], s[6:7], 11
	v_ashrrev_i32_e32 v44, 3, v202
	v_lshlrev_b32_e32 v0, 3, v202
	s_add_u32 s16, s14, s16
	v_and_b32_e32 v45, 56, v0
	v_lshlrev_b32_e32 v0, 11, v44
	s_addc_u32 s17, s15, s17
	v_lshl_or_b32 v200, v45, 1, v0
	v_lshl_add_u64 v[12:13], s[16:17], 0, v[200:201]
	v_add_co_u32_e32 v32, vcc, s37, v12
	s_lshl_b32 s19, s59, 11
	s_nop 0
	v_addc_co_u32_e32 v33, vcc, 0, v13, vcc
	v_add_co_u32_e32 v34, vcc, s38, v12
	s_add_u32 s20, s22, s19
	s_nop 0
	v_addc_co_u32_e32 v35, vcc, 0, v13, vcc
	v_add_co_u32_e32 v36, vcc, s39, v12
	s_addc_u32 s21, s23, 0
	s_nop 0
	v_addc_co_u32_e32 v37, vcc, 0, v13, vcc
	v_lshl_add_u64 v[28:29], s[20:21], 0, v[200:201]
	v_add_co_u32_e32 v38, vcc, s37, v28
	global_load_dwordx4 v[0:3], v200, s[16:17]
	global_load_dwordx4 v[16:19], v200, s[20:21]
	v_addc_co_u32_e32 v39, vcc, 0, v29, vcc
	v_add_co_u32_e32 v40, vcc, s38, v28
	global_load_dwordx4 v[4:7], v[32:33], off
	global_load_dwordx4 v[8:11], v[34:35], off
	v_addc_co_u32_e32 v41, vcc, 0, v29, vcc
	v_add_co_u32_e32 v42, vcc, s39, v28
	global_load_dwordx4 v[12:15], v[36:37], off
	global_load_dwordx4 v[20:23], v[38:39], off
	v_addc_co_u32_e32 v43, vcc, 0, v29, vcc
	global_load_dwordx4 v[24:27], v[40:41], off
	global_load_dwordx4 v[28:31], v[42:43], off
	global_load_dwordx4 v[64:67], v200, s[16:17] offset:128
	global_load_dwordx4 v[68:71], v[32:33], off offset:128
	global_load_dwordx4 v[72:75], v[34:35], off offset:128
	global_load_dwordx4 v[76:79], v[36:37], off offset:128
	global_load_dwordx4 v[88:91], v200, s[20:21] offset:128
	global_load_dwordx4 v[96:99], v[38:39], off offset:128
	global_load_dwordx4 v[104:107], v[40:41], off offset:128
	global_load_dwordx4 v[108:111], v[42:43], off offset:128
	s_waitcnt lgkmcnt(0)
	s_barrier
	global_load_dwordx4 v[84:87], v[32:33], off offset:256
	global_load_dwordx4 v[92:95], v[34:35], off offset:256
	global_load_dwordx4 v[80:83], v200, s[16:17] offset:256
	global_load_dwordx4 v[112:115], v200, s[20:21] offset:256
	global_load_dwordx4 v[100:103], v[36:37], off offset:256
	global_load_dwordx4 v[116:119], v[38:39], off offset:256
	global_load_dwordx4 v[120:123], v[40:41], off offset:256
	global_load_dwordx4 v[124:127], v[42:43], off offset:256
	v_mul_lo_u32 v44, v44, s36
	v_add_lshl_u32 v206, v44, v45, 1
	v_and_b32_e32 v203, 31, v202
	v_bfe_u32 v204, v202, 5, 1
	s_mov_b32 s19, 0
	s_waitcnt vmcnt(0)
	ds_write_b128 v206, v[0:3]
	ds_write_b128 v206, v[4:7] offset:4608
	ds_write_b128 v206, v[8:11] offset:9216
	ds_write_b128 v206, v[12:15] offset:13824
	ds_write_b128 v206, v[16:19] offset:18432
	ds_write_b128 v206, v[20:23] offset:23040
	ds_write_b128 v206, v[24:27] offset:27648
	ds_write_b128 v206, v[28:31] offset:32256
	v_ashrrev_i32_e32 v0, 1, v202
	v_and_b32_e32 v205, 0xffffffc0, v0
	v_or_b32_e32 v0, v205, v203
	v_and_b32_e32 v2, 0x5f, v202
	v_lshlrev_b32_e32 v1, 4, v204
	v_mul_u32_u24_e32 v2, 0x90, v2
	v_mul_lo_u32 v3, v0, s40
	v_mov_b32_e32 v0, 0
	v_add_u32_e32 v207, v1, v3
	v_add_u32_e32 v208, v1, v2
	v_mov_b32_e32 v1, v0
	v_mov_b32_e32 v2, v0
	v_mov_b32_e32 v3, v0
	v_mov_b32_e32 v4, v0
	v_mov_b32_e32 v5, v0
	v_mov_b32_e32 v6, v0
	v_mov_b32_e32 v7, v0
	v_mov_b32_e32 v8, v0
	v_mov_b32_e32 v9, v0
	v_mov_b32_e32 v10, v0
	v_mov_b32_e32 v11, v0
	v_mov_b32_e32 v12, v0
	v_mov_b32_e32 v13, v0
	v_mov_b32_e32 v14, v0
	v_mov_b32_e32 v15, v0
	v_mov_b32_e32 v32, v0
	v_mov_b32_e32 v33, v0
	v_mov_b32_e32 v34, v0
	v_mov_b32_e32 v35, v0
	v_mov_b32_e32 v36, v0
	v_mov_b32_e32 v37, v0
	v_mov_b32_e32 v38, v0
	v_mov_b32_e32 v39, v0
	v_mov_b32_e32 v40, v0
	v_mov_b32_e32 v41, v0
	v_mov_b32_e32 v42, v0
	v_mov_b32_e32 v43, v0
	v_mov_b32_e32 v44, v0
	v_mov_b32_e32 v45, v0
	v_mov_b32_e32 v46, v0
	v_mov_b32_e32 v47, v0
	v_mov_b32_e32 v16, v0
	v_mov_b32_e32 v17, v0
	v_mov_b32_e32 v18, v0
	v_mov_b32_e32 v19, v0
	v_mov_b32_e32 v20, v0
	v_mov_b32_e32 v21, v0
	v_mov_b32_e32 v22, v0
	v_mov_b32_e32 v23, v0
	v_mov_b32_e32 v24, v0
	v_mov_b32_e32 v25, v0
	v_mov_b32_e32 v26, v0
	v_mov_b32_e32 v27, v0
	v_mov_b32_e32 v28, v0
	v_mov_b32_e32 v29, v0
	v_mov_b32_e32 v30, v0
	v_mov_b32_e32 v31, v0
	v_mov_b32_e32 v48, v0
	v_mov_b32_e32 v49, v0
	v_mov_b32_e32 v50, v0
	v_mov_b32_e32 v51, v0
	v_mov_b32_e32 v52, v0
	v_mov_b32_e32 v53, v0
	v_mov_b32_e32 v54, v0
	v_mov_b32_e32 v55, v0
	v_mov_b32_e32 v56, v0
	v_mov_b32_e32 v57, v0
	v_mov_b32_e32 v58, v0
	v_mov_b32_e32 v59, v0
	v_mov_b32_e32 v60, v0
	v_mov_b32_e32 v61, v0
	v_mov_b32_e32 v62, v0
	v_mov_b32_e32 v63, v0
	s_waitcnt lgkmcnt(0)
	s_barrier
	v_add_u32_e32 v209, 0x2957000, v200
	v_add_u32_e32 v210, 0x2967000, v200
	v_add_u32_e32 v211, 0x2977000, v200
	v_add_u32_e32 v212, 0x2987000, v200
	v_add_u32_e32 v213, 0x4c0000, v200
	v_add_u32_e32 v214, 0x4d0000, v200
	v_add_u32_e32 v215, 0x4e0000, v200
	v_add_u32_e32 v216, 0x4f0000, v200
	s_branch .LBB0_834

.LBB0_834:
	ds_read_b128 v[176:179], v207
	ds_read_b128 v[144:147], v207 offset:32
	ds_read_b128 v[184:187], v208 offset:18432
	ds_read_b128 v[148:151], v208 offset:18464
	ds_read_b128 v[180:183], v207 offset:4608
	ds_read_b128 v[156:159], v207 offset:4640
	ds_read_b128 v[188:191], v208 offset:23040
	ds_read_b128 v[164:167], v208 offset:23072
	ds_read_b128 v[152:155], v207 offset:64
	ds_read_b128 v[128:131], v207 offset:96
	ds_read_b128 v[160:163], v207 offset:4672
	ds_read_b128 v[136:139], v207 offset:4704
	ds_read_b128 v[168:171], v208 offset:18496
	ds_read_b128 v[132:135], v208 offset:18528
	ds_read_b128 v[172:175], v208 offset:23104
	ds_read_b128 v[140:143], v208 offset:23136
	s_cmp_lt_u32 s19, 13
	s_waitcnt lgkmcnt(0)
	s_barrier
	s_waitcnt vmcnt(7)
	ds_write_b128 v206, v[64:67]
	s_waitcnt vmcnt(6)
	ds_write_b128 v206, v[68:71] offset:4608
	s_waitcnt vmcnt(5)
	ds_write_b128 v206, v[72:75] offset:9216
	s_waitcnt vmcnt(4)
	ds_write_b128 v206, v[76:79] offset:13824
	s_waitcnt vmcnt(3)
	ds_write_b128 v206, v[88:91] offset:18432
	s_waitcnt vmcnt(2)
	ds_write_b128 v206, v[96:99] offset:23040
	s_waitcnt vmcnt(1)
	ds_write_b128 v206, v[104:107] offset:27648
	s_waitcnt vmcnt(0)
	ds_write_b128 v206, v[108:111] offset:32256
	s_cbranch_scc0 .LBB0_836
	global_load_dwordx4 v[64:67], v209, s[12:13] offset:2688
	global_load_dwordx4 v[68:71], v210, s[12:13] offset:2688
	global_load_dwordx4 v[72:75], v211, s[12:13] offset:2688
	global_load_dwordx4 v[76:79], v212, s[12:13] offset:2688
	global_load_dwordx4 v[88:91], v213, s[10:11] offset:384
	global_load_dwordx4 v[96:99], v214, s[10:11] offset:384
	global_load_dwordx4 v[104:107], v215, s[10:11] offset:384
	global_load_dwordx4 v[108:111], v216, s[10:11] offset:384
.LBB0_836:
	v_mfma_f32_32x32x16_bf16 v[48:63], v[176:179], v[184:187], v[48:63]
	s_waitcnt lgkmcnt(0)
	s_barrier
	s_cmp_gt_u32 s19, 13
	s_cselect_b64 s[16:17], -1, 0
	s_and_b64 vcc, exec, s[16:17]
	v_mfma_f32_32x32x16_bf16 v[16:31], v[176:179], v[188:191], v[16:31]
	v_mfma_f32_32x32x16_bf16 v[32:47], v[180:183], v[184:187], v[32:47]
	v_mfma_f32_32x32x16_bf16 v[0:15], v[180:183], v[188:191], v[0:15]
	v_mfma_f32_32x32x16_bf16 v[48:63], v[144:147], v[148:151], v[48:63]
	v_mfma_f32_32x32x16_bf16 v[16:31], v[144:147], v[164:167], v[16:31]
	v_mfma_f32_32x32x16_bf16 v[32:47], v[156:159], v[148:151], v[32:47]
	v_mfma_f32_32x32x16_bf16 v[0:15], v[156:159], v[164:167], v[0:15]
	v_mfma_f32_32x32x16_bf16 v[48:63], v[152:155], v[168:171], v[48:63]
	v_mfma_f32_32x32x16_bf16 v[16:31], v[152:155], v[172:175], v[16:31]
	v_mfma_f32_32x32x16_bf16 v[32:47], v[160:163], v[168:171], v[32:47]
	v_mfma_f32_32x32x16_bf16 v[0:15], v[160:163], v[172:175], v[0:15]
	ds_read_b128 v[176:179], v207
	ds_read_b128 v[152:155], v207 offset:32
	ds_read_b128 v[188:191], v208 offset:18432
	ds_read_b128 v[156:159], v208 offset:18464
	ds_read_b128 v[184:187], v207 offset:4608
	ds_read_b128 v[160:163], v207 offset:4640
	v_mfma_f32_32x32x16_bf16 v[48:63], v[128:131], v[132:135], v[48:63]
	v_mfma_f32_32x32x16_bf16 v[16:31], v[128:131], v[140:143], v[16:31]
	ds_read_b128 v[196:199], v208 offset:23040
	ds_read_b128 v[172:175], v208 offset:23072
	ds_read_b128 v[164:167], v207 offset:64
	ds_read_b128 v[148:151], v207 offset:96
	ds_read_b128 v[168:171], v207 offset:4672
	ds_read_b128 v[128:131], v207 offset:4704
	ds_read_b128 v[180:183], v208 offset:18496
	ds_read_b128 v[144:147], v208 offset:18528
	v_mfma_f32_32x32x16_bf16 v[32:47], v[136:139], v[132:135], v[32:47]
	ds_read_b128 v[192:195], v208 offset:23104
	ds_read_b128 v[132:135], v208 offset:23136
	s_waitcnt lgkmcnt(0)
	s_barrier
	v_mfma_f32_32x32x16_bf16 v[0:15], v[136:139], v[140:143], v[0:15]
	s_cbranch_vccnz .LBB0_833
	s_cmp_gt_u32 s19, 11
	ds_write_b128 v206, v[80:83]
	ds_write_b128 v206, v[84:87] offset:4608
	ds_write_b128 v206, v[92:95] offset:9216
	ds_write_b128 v206, v[100:103] offset:13824
	ds_write_b128 v206, v[112:115] offset:18432
	ds_write_b128 v206, v[116:119] offset:23040
	ds_write_b128 v206, v[120:123] offset:27648
	ds_write_b128 v206, v[124:127] offset:32256
	s_cbranch_scc1 .LBB0_833
	global_load_dwordx4 v[80:83], v209, s[12:13] offset:2816
	global_load_dwordx4 v[84:87], v210, s[12:13] offset:2816
	global_load_dwordx4 v[92:95], v211, s[12:13] offset:2816
	global_load_dwordx4 v[100:103], v212, s[12:13] offset:2816
	global_load_dwordx4 v[112:115], v213, s[10:11] offset:512
	global_load_dwordx4 v[116:119], v214, s[10:11] offset:512
	global_load_dwordx4 v[120:123], v215, s[10:11] offset:512
	global_load_dwordx4 v[124:127], v216, s[10:11] offset:512
	s_branch .LBB0_833

.LBB0_1065:
	s_lshl_b32 s0, s60, 13
	s_and_b32 s0, s0, 0x700000
	s_add_u32 s10, s30, s0
	s_addc_u32 s11, s31, 0
	s_lshr_b32 s18, s61, 3
	s_lshl_b32 s0, s18, 7
	s_add_i32 s0, s37, s0
	s_lshl_b64 s[8:9], s[0:1], 13
	s_add_u32 s12, s30, s8
	s_addc_u32 s13, s31, s9
	s_lshl_b32 s8, s61, 7
	s_and_b32 s62, s8, 0x380
	s_mov_b64 s[8:9], s[30:31]
	v_mov_b32_e32 v0, v201
	s_add_i32 s18, s18, s25
	v_mbcnt_lo_u32_b32 v0, -1, v0
	v_mbcnt_hi_u32_b32 v0, -1, v0
	s_lshl_b32 s0, s18, 7
	v_add_u32_e32 v202, s33, v0
	s_lshl_b64 s[16:17], s[0:1], 13
	v_ashrrev_i32_e32 v44, 3, v202
	v_lshlrev_b32_e32 v0, 3, v202
	s_add_u32 s16, s26, s16
	v_and_b32_e32 v45, 56, v0
	v_lshlrev_b32_e32 v0, 13, v44
	s_addc_u32 s17, s27, s17
	v_lshl_or_b32 v200, v45, 1, v0
	v_lshl_add_u64 v[12:13], s[16:17], 0, v[200:201]
	v_add_co_u32_e32 v32, vcc, s39, v12
	s_lshl_b32 s19, s62, 13
	s_nop 0
	v_addc_co_u32_e32 v33, vcc, 0, v13, vcc
	v_add_co_u32_e32 v34, vcc, s40, v12
	s_add_u32 s20, s22, s19
	s_nop 0
	v_addc_co_u32_e32 v35, vcc, 0, v13, vcc
	v_add_co_u32_e32 v36, vcc, s41, v12
	s_addc_u32 s21, s23, 0
	s_nop 0
	v_addc_co_u32_e32 v37, vcc, 0, v13, vcc
	v_lshl_add_u64 v[28:29], s[20:21], 0, v[200:201]
	v_add_co_u32_e32 v38, vcc, s39, v28
	global_load_dwordx4 v[0:3], v200, s[16:17]
	global_load_dwordx4 v[16:19], v200, s[20:21]
	v_addc_co_u32_e32 v39, vcc, 0, v29, vcc
	v_add_co_u32_e32 v40, vcc, s40, v28
	global_load_dwordx4 v[4:7], v[32:33], off
	global_load_dwordx4 v[8:11], v[34:35], off
	v_addc_co_u32_e32 v41, vcc, 0, v29, vcc
	v_add_co_u32_e32 v42, vcc, s41, v28
	global_load_dwordx4 v[12:15], v[36:37], off
	global_load_dwordx4 v[20:23], v[38:39], off
	v_addc_co_u32_e32 v43, vcc, 0, v29, vcc
	global_load_dwordx4 v[24:27], v[40:41], off
	global_load_dwordx4 v[28:31], v[42:43], off
	global_load_dwordx4 v[64:67], v200, s[16:17] offset:128
	global_load_dwordx4 v[68:71], v[32:33], off offset:128
	global_load_dwordx4 v[72:75], v[34:35], off offset:128
	global_load_dwordx4 v[76:79], v[36:37], off offset:128
	global_load_dwordx4 v[88:91], v200, s[20:21] offset:128
	global_load_dwordx4 v[96:99], v[38:39], off offset:128
	global_load_dwordx4 v[104:107], v[40:41], off offset:128
	global_load_dwordx4 v[108:111], v[42:43], off offset:128
	s_waitcnt lgkmcnt(0)
	s_barrier
	global_load_dwordx4 v[84:87], v[32:33], off offset:256
	global_load_dwordx4 v[92:95], v[34:35], off offset:256
	global_load_dwordx4 v[80:83], v200, s[16:17] offset:256
	global_load_dwordx4 v[112:115], v200, s[20:21] offset:256
	global_load_dwordx4 v[100:103], v[36:37], off offset:256
	global_load_dwordx4 v[116:119], v[38:39], off offset:256
	global_load_dwordx4 v[120:123], v[40:41], off offset:256
	global_load_dwordx4 v[124:127], v[42:43], off offset:256
	v_mul_lo_u32 v44, v44, s38
	v_add_lshl_u32 v206, v44, v45, 1
	v_and_b32_e32 v203, 31, v202
	v_bfe_u32 v204, v202, 5, 1
	s_mov_b32 s19, 0
	s_waitcnt vmcnt(0)
	ds_write_b128 v206, v[0:3]
	ds_write_b128 v206, v[4:7] offset:4608
	ds_write_b128 v206, v[8:11] offset:9216
	ds_write_b128 v206, v[12:15] offset:13824
	ds_write_b128 v206, v[16:19] offset:18432
	ds_write_b128 v206, v[20:23] offset:23040
	ds_write_b128 v206, v[24:27] offset:27648
	ds_write_b128 v206, v[28:31] offset:32256
	v_ashrrev_i32_e32 v0, 1, v202
	v_and_b32_e32 v205, 0xffffffc0, v0
	v_or_b32_e32 v0, v205, v203
	v_and_b32_e32 v2, 0x5f, v202
	v_lshlrev_b32_e32 v1, 4, v204
	v_mul_u32_u24_e32 v2, 0x90, v2
	v_mul_lo_u32 v3, v0, s42
	v_mov_b32_e32 v0, 0
	v_add_u32_e32 v207, v1, v3
	v_add_u32_e32 v208, v1, v2
	v_mov_b32_e32 v1, v0
	v_mov_b32_e32 v2, v0
	v_mov_b32_e32 v3, v0
	v_mov_b32_e32 v4, v0
	v_mov_b32_e32 v5, v0
	v_mov_b32_e32 v6, v0
	v_mov_b32_e32 v7, v0
	v_mov_b32_e32 v8, v0
	v_mov_b32_e32 v9, v0
	v_mov_b32_e32 v10, v0
	v_mov_b32_e32 v11, v0
	v_mov_b32_e32 v12, v0
	v_mov_b32_e32 v13, v0
	v_mov_b32_e32 v14, v0
	v_mov_b32_e32 v15, v0
	v_mov_b32_e32 v32, v0
	v_mov_b32_e32 v33, v0
	v_mov_b32_e32 v34, v0
	v_mov_b32_e32 v35, v0
	v_mov_b32_e32 v36, v0
	v_mov_b32_e32 v37, v0
	v_mov_b32_e32 v38, v0
	v_mov_b32_e32 v39, v0
	v_mov_b32_e32 v40, v0
	v_mov_b32_e32 v41, v0
	v_mov_b32_e32 v42, v0
	v_mov_b32_e32 v43, v0
	v_mov_b32_e32 v44, v0
	v_mov_b32_e32 v45, v0
	v_mov_b32_e32 v46, v0
	v_mov_b32_e32 v47, v0
	v_mov_b32_e32 v16, v0
	v_mov_b32_e32 v17, v0
	v_mov_b32_e32 v18, v0
	v_mov_b32_e32 v19, v0
	v_mov_b32_e32 v20, v0
	v_mov_b32_e32 v21, v0
	v_mov_b32_e32 v22, v0
	v_mov_b32_e32 v23, v0
	v_mov_b32_e32 v24, v0
	v_mov_b32_e32 v25, v0
	v_mov_b32_e32 v26, v0
	v_mov_b32_e32 v27, v0
	v_mov_b32_e32 v28, v0
	v_mov_b32_e32 v29, v0
	v_mov_b32_e32 v30, v0
	v_mov_b32_e32 v31, v0
	v_mov_b32_e32 v48, v0
	v_mov_b32_e32 v49, v0
	v_mov_b32_e32 v50, v0
	v_mov_b32_e32 v51, v0
	v_mov_b32_e32 v52, v0
	v_mov_b32_e32 v53, v0
	v_mov_b32_e32 v54, v0
	v_mov_b32_e32 v55, v0
	v_mov_b32_e32 v56, v0
	v_mov_b32_e32 v57, v0
	v_mov_b32_e32 v58, v0
	v_mov_b32_e32 v59, v0
	v_mov_b32_e32 v60, v0
	v_mov_b32_e32 v61, v0
	v_mov_b32_e32 v62, v0
	v_mov_b32_e32 v63, v0
	s_waitcnt lgkmcnt(0)
	s_barrier
	v_add_u32_e32 v209, 0x7157000, v200
	v_add_u32_e32 v210, 0x7197000, v200
	v_add_u32_e32 v211, 0x71d7000, v200
	v_add_u32_e32 v212, 0x7217000, v200
	v_add_u32_e32 v213, 0xec0000, v200
	v_add_u32_e32 v214, 0xf00000, v200
	v_add_u32_e32 v215, 0xf40000, v200
	v_add_u32_e32 v216, 0xf80000, v200
	s_branch .LBB0_1067

.LBB0_1067:
	ds_read_b128 v[176:179], v207
	ds_read_b128 v[144:147], v207 offset:32
	ds_read_b128 v[184:187], v208 offset:18432
	ds_read_b128 v[148:151], v208 offset:18464
	ds_read_b128 v[180:183], v207 offset:4608
	ds_read_b128 v[156:159], v207 offset:4640
	ds_read_b128 v[188:191], v208 offset:23040
	ds_read_b128 v[164:167], v208 offset:23072
	ds_read_b128 v[152:155], v207 offset:64
	ds_read_b128 v[128:131], v207 offset:96
	ds_read_b128 v[160:163], v207 offset:4672
	ds_read_b128 v[136:139], v207 offset:4704
	ds_read_b128 v[168:171], v208 offset:18496
	ds_read_b128 v[132:135], v208 offset:18528
	ds_read_b128 v[172:175], v208 offset:23104
	ds_read_b128 v[140:143], v208 offset:23136
	s_cmp_lt_u32 s19, 61
	s_waitcnt lgkmcnt(0)
	s_barrier
	s_waitcnt vmcnt(7)
	ds_write_b128 v206, v[64:67]
	s_waitcnt vmcnt(6)
	ds_write_b128 v206, v[68:71] offset:4608
	s_waitcnt vmcnt(5)
	ds_write_b128 v206, v[72:75] offset:9216
	s_waitcnt vmcnt(4)
	ds_write_b128 v206, v[76:79] offset:13824
	s_waitcnt vmcnt(3)
	ds_write_b128 v206, v[88:91] offset:18432
	s_waitcnt vmcnt(2)
	ds_write_b128 v206, v[96:99] offset:23040
	s_waitcnt vmcnt(1)
	ds_write_b128 v206, v[104:107] offset:27648
	s_waitcnt vmcnt(0)
	ds_write_b128 v206, v[108:111] offset:32256
	s_cbranch_scc0 .LBB0_1069
	global_load_dwordx4 v[64:67], v209, s[12:13] offset:2688
	global_load_dwordx4 v[68:71], v210, s[12:13] offset:2688
	global_load_dwordx4 v[72:75], v211, s[12:13] offset:2688
	global_load_dwordx4 v[76:79], v212, s[12:13] offset:2688
	global_load_dwordx4 v[88:91], v213, s[10:11] offset:384
	global_load_dwordx4 v[96:99], v214, s[10:11] offset:384
	global_load_dwordx4 v[104:107], v215, s[10:11] offset:384
	global_load_dwordx4 v[108:111], v216, s[10:11] offset:384
.LBB0_1069:
	v_mfma_f32_32x32x16_bf16 v[48:63], v[176:179], v[184:187], v[48:63]
	s_waitcnt lgkmcnt(0)
	s_barrier
	s_cmp_gt_u32 s19, 61
	s_cselect_b64 s[16:17], -1, 0
	s_and_b64 vcc, exec, s[16:17]
	v_mfma_f32_32x32x16_bf16 v[16:31], v[176:179], v[188:191], v[16:31]
	v_mfma_f32_32x32x16_bf16 v[32:47], v[180:183], v[184:187], v[32:47]
	v_mfma_f32_32x32x16_bf16 v[0:15], v[180:183], v[188:191], v[0:15]
	v_mfma_f32_32x32x16_bf16 v[48:63], v[144:147], v[148:151], v[48:63]
	v_mfma_f32_32x32x16_bf16 v[16:31], v[144:147], v[164:167], v[16:31]
	v_mfma_f32_32x32x16_bf16 v[32:47], v[156:159], v[148:151], v[32:47]
	v_mfma_f32_32x32x16_bf16 v[0:15], v[156:159], v[164:167], v[0:15]
	v_mfma_f32_32x32x16_bf16 v[48:63], v[152:155], v[168:171], v[48:63]
	v_mfma_f32_32x32x16_bf16 v[16:31], v[152:155], v[172:175], v[16:31]
	v_mfma_f32_32x32x16_bf16 v[32:47], v[160:163], v[168:171], v[32:47]
	v_mfma_f32_32x32x16_bf16 v[0:15], v[160:163], v[172:175], v[0:15]
	ds_read_b128 v[176:179], v207
	ds_read_b128 v[152:155], v207 offset:32
	ds_read_b128 v[188:191], v208 offset:18432
	ds_read_b128 v[156:159], v208 offset:18464
	ds_read_b128 v[184:187], v207 offset:4608
	ds_read_b128 v[160:163], v207 offset:4640
	v_mfma_f32_32x32x16_bf16 v[48:63], v[128:131], v[132:135], v[48:63]
	v_mfma_f32_32x32x16_bf16 v[16:31], v[128:131], v[140:143], v[16:31]
	ds_read_b128 v[196:199], v208 offset:23040
	ds_read_b128 v[172:175], v208 offset:23072
	ds_read_b128 v[164:167], v207 offset:64
	ds_read_b128 v[148:151], v207 offset:96
	ds_read_b128 v[168:171], v207 offset:4672
	ds_read_b128 v[128:131], v207 offset:4704
	ds_read_b128 v[180:183], v208 offset:18496
	ds_read_b128 v[144:147], v208 offset:18528
	v_mfma_f32_32x32x16_bf16 v[32:47], v[136:139], v[132:135], v[32:47]
	ds_read_b128 v[192:195], v208 offset:23104
	ds_read_b128 v[132:135], v208 offset:23136
	s_waitcnt lgkmcnt(0)
	s_barrier
	v_mfma_f32_32x32x16_bf16 v[0:15], v[136:139], v[140:143], v[0:15]
	s_cbranch_vccnz .LBB0_1066
	s_cmp_gt_u32 s19, 59
	ds_write_b128 v206, v[80:83]
	ds_write_b128 v206, v[84:87] offset:4608
	ds_write_b128 v206, v[92:95] offset:9216
	ds_write_b128 v206, v[100:103] offset:13824
	ds_write_b128 v206, v[112:115] offset:18432
	ds_write_b128 v206, v[116:119] offset:23040
	ds_write_b128 v206, v[120:123] offset:27648
	ds_write_b128 v206, v[124:127] offset:32256
	s_cbranch_scc1 .LBB0_1066
	global_load_dwordx4 v[80:83], v209, s[12:13] offset:2816
	global_load_dwordx4 v[84:87], v210, s[12:13] offset:2816
	global_load_dwordx4 v[92:95], v211, s[12:13] offset:2816
	global_load_dwordx4 v[100:103], v212, s[12:13] offset:2816
	global_load_dwordx4 v[112:115], v213, s[10:11] offset:512
	global_load_dwordx4 v[116:119], v214, s[10:11] offset:512
	global_load_dwordx4 v[120:123], v215, s[10:11] offset:512
	global_load_dwordx4 v[124:127], v216, s[10:11] offset:512
	s_branch .LBB0_1066

.LBB0_1812:
	s_lshl_b32 s6, s56, 11
	s_and_b32 s6, s6, 0x1c0000
	s_add_u32 s10, s30, s6
	s_addc_u32 s11, s31, 0
	s_lshr_b32 s6, s57, 3
	s_add_i32 s6, s25, s6
	s_lshr_b32 s6, s6, 4
	s_mul_i32 s6, s6, 18
	s_bfe_u32 s8, s57, 0x40003
	s_add_i32 s18, s6, s8
	s_add_i32 s18, s18, 2
	s_lshl_b32 s6, s18, 7
	s_lshl_b64 s[16:17], s[6:7], 11
	s_add_u32 s12, s30, s16
	s_addc_u32 s13, s31, s17
	s_lshl_b32 s8, s57, 7
	s_and_b32 s58, s8, 0x380
	s_mov_b64 s[8:9], s[30:31]
	v_mov_b32_e32 v0, v201
	s_add_u32 s16, s14, s16
	v_mbcnt_lo_u32_b32 v0, -1, v0
	v_mbcnt_hi_u32_b32 v0, -1, v0
	v_add_u32_e32 v202, s33, v0
	s_addc_u32 s17, s15, s17
	v_ashrrev_i32_e32 v44, 3, v202
	v_lshlrev_b32_e32 v0, 3, v202
	v_and_b32_e32 v45, 56, v0
	v_lshlrev_b32_e32 v0, 11, v44
	v_lshl_or_b32 v200, v45, 1, v0
	v_lshl_add_u64 v[12:13], s[16:17], 0, v[200:201]
	v_add_co_u32_e32 v32, vcc, s36, v12
	s_lshl_b32 s19, s58, 11
	s_nop 0
	v_addc_co_u32_e32 v33, vcc, 0, v13, vcc
	v_add_co_u32_e32 v34, vcc, s37, v12
	s_add_u32 s20, s22, s19
	s_nop 0
	v_addc_co_u32_e32 v35, vcc, 0, v13, vcc
	v_add_co_u32_e32 v36, vcc, s38, v12
	s_addc_u32 s21, s23, 0
	s_nop 0
	v_addc_co_u32_e32 v37, vcc, 0, v13, vcc
	v_lshl_add_u64 v[28:29], s[20:21], 0, v[200:201]
	v_add_co_u32_e32 v38, vcc, s36, v28
	global_load_dwordx4 v[0:3], v200, s[16:17]
	global_load_dwordx4 v[16:19], v200, s[20:21]
	v_addc_co_u32_e32 v39, vcc, 0, v29, vcc
	v_add_co_u32_e32 v40, vcc, s37, v28
	global_load_dwordx4 v[4:7], v[32:33], off
	global_load_dwordx4 v[8:11], v[34:35], off
	v_addc_co_u32_e32 v41, vcc, 0, v29, vcc
	v_add_co_u32_e32 v42, vcc, s38, v28
	global_load_dwordx4 v[12:15], v[36:37], off
	global_load_dwordx4 v[20:23], v[38:39], off
	v_addc_co_u32_e32 v43, vcc, 0, v29, vcc
	global_load_dwordx4 v[24:27], v[40:41], off
	global_load_dwordx4 v[28:31], v[42:43], off
	global_load_dwordx4 v[64:67], v200, s[16:17] offset:128
	global_load_dwordx4 v[68:71], v[32:33], off offset:128
	global_load_dwordx4 v[72:75], v[34:35], off offset:128
	global_load_dwordx4 v[76:79], v[36:37], off offset:128
	global_load_dwordx4 v[88:91], v200, s[20:21] offset:128
	global_load_dwordx4 v[96:99], v[38:39], off offset:128
	global_load_dwordx4 v[104:107], v[40:41], off offset:128
	global_load_dwordx4 v[108:111], v[42:43], off offset:128
	s_waitcnt lgkmcnt(0)
	s_barrier
	global_load_dwordx4 v[84:87], v[32:33], off offset:256
	global_load_dwordx4 v[92:95], v[34:35], off offset:256
	global_load_dwordx4 v[80:83], v200, s[16:17] offset:256
	global_load_dwordx4 v[112:115], v200, s[20:21] offset:256
	global_load_dwordx4 v[100:103], v[36:37], off offset:256
	global_load_dwordx4 v[116:119], v[38:39], off offset:256
	global_load_dwordx4 v[120:123], v[40:41], off offset:256
	global_load_dwordx4 v[124:127], v[42:43], off offset:256
	v_mul_lo_u32 v44, v44, s35
	v_add_lshl_u32 v206, v44, v45, 1
	v_and_b32_e32 v203, 31, v202
	v_bfe_u32 v204, v202, 5, 1
	s_mov_b32 s19, 0
	s_waitcnt vmcnt(0)
	ds_write_b128 v206, v[0:3]
	ds_write_b128 v206, v[4:7] offset:4608
	ds_write_b128 v206, v[8:11] offset:9216
	ds_write_b128 v206, v[12:15] offset:13824
	ds_write_b128 v206, v[16:19] offset:18432
	ds_write_b128 v206, v[20:23] offset:23040
	ds_write_b128 v206, v[24:27] offset:27648
	ds_write_b128 v206, v[28:31] offset:32256
	v_ashrrev_i32_e32 v0, 1, v202
	v_and_b32_e32 v205, 0xffffffc0, v0
	v_or_b32_e32 v0, v205, v203
	v_and_b32_e32 v2, 0x5f, v202
	v_lshlrev_b32_e32 v1, 4, v204
	v_mul_u32_u24_e32 v2, 0x90, v2
	v_mul_lo_u32 v3, v0, s39
	v_mov_b32_e32 v0, 0
	v_add_u32_e32 v207, v1, v3
	v_add_u32_e32 v208, v1, v2
	v_mov_b32_e32 v1, v0
	v_mov_b32_e32 v2, v0
	v_mov_b32_e32 v3, v0
	v_mov_b32_e32 v4, v0
	v_mov_b32_e32 v5, v0
	v_mov_b32_e32 v6, v0
	v_mov_b32_e32 v7, v0
	v_mov_b32_e32 v8, v0
	v_mov_b32_e32 v9, v0
	v_mov_b32_e32 v10, v0
	v_mov_b32_e32 v11, v0
	v_mov_b32_e32 v12, v0
	v_mov_b32_e32 v13, v0
	v_mov_b32_e32 v14, v0
	v_mov_b32_e32 v15, v0
	v_mov_b32_e32 v32, v0
	v_mov_b32_e32 v33, v0
	v_mov_b32_e32 v34, v0
	v_mov_b32_e32 v35, v0
	v_mov_b32_e32 v36, v0
	v_mov_b32_e32 v37, v0
	v_mov_b32_e32 v38, v0
	v_mov_b32_e32 v39, v0
	v_mov_b32_e32 v40, v0
	v_mov_b32_e32 v41, v0
	v_mov_b32_e32 v42, v0
	v_mov_b32_e32 v43, v0
	v_mov_b32_e32 v44, v0
	v_mov_b32_e32 v45, v0
	v_mov_b32_e32 v46, v0
	v_mov_b32_e32 v47, v0
	v_mov_b32_e32 v16, v0
	v_mov_b32_e32 v17, v0
	v_mov_b32_e32 v18, v0
	v_mov_b32_e32 v19, v0
	v_mov_b32_e32 v20, v0
	v_mov_b32_e32 v21, v0
	v_mov_b32_e32 v22, v0
	v_mov_b32_e32 v23, v0
	v_mov_b32_e32 v24, v0
	v_mov_b32_e32 v25, v0
	v_mov_b32_e32 v26, v0
	v_mov_b32_e32 v27, v0
	v_mov_b32_e32 v28, v0
	v_mov_b32_e32 v29, v0
	v_mov_b32_e32 v30, v0
	v_mov_b32_e32 v31, v0
	v_mov_b32_e32 v48, v0
	v_mov_b32_e32 v49, v0
	v_mov_b32_e32 v50, v0
	v_mov_b32_e32 v51, v0
	v_mov_b32_e32 v52, v0
	v_mov_b32_e32 v53, v0
	v_mov_b32_e32 v54, v0
	v_mov_b32_e32 v55, v0
	v_mov_b32_e32 v56, v0
	v_mov_b32_e32 v57, v0
	v_mov_b32_e32 v58, v0
	v_mov_b32_e32 v59, v0
	v_mov_b32_e32 v60, v0
	v_mov_b32_e32 v61, v0
	v_mov_b32_e32 v62, v0
	v_mov_b32_e32 v63, v0
	s_waitcnt lgkmcnt(0)
	s_barrier
	v_add_u32_e32 v209, 0x2957000, v200
	v_add_u32_e32 v210, 0x2967000, v200
	v_add_u32_e32 v211, 0x2977000, v200
	v_add_u32_e32 v212, 0x2987000, v200
	v_add_u32_e32 v213, 0x4c0000, v200
	v_add_u32_e32 v214, 0x4d0000, v200
	v_add_u32_e32 v215, 0x4e0000, v200
	v_add_u32_e32 v216, 0x4f0000, v200
	s_branch .LBB0_1814

.LBB0_2045:
	s_lshl_b32 s0, s57, 13
	s_and_b32 s0, s0, 0x700000
	s_add_u32 s10, s30, s0
	s_addc_u32 s11, s31, 0
	s_lshr_b32 s0, s58, 3
	s_add_i32 s0, s23, s0
	s_lshr_b32 s0, s0, 4
	s_mul_i32 s0, s0, 18
	s_bfe_u32 s8, s58, 0x40003
	s_add_i32 s16, s0, s8
	s_add_i32 s16, s16, 2
	s_lshl_b32 s0, s16, 7
	s_lshl_b64 s[14:15], s[0:1], 13
	s_add_u32 s12, s30, s14
	s_addc_u32 s13, s31, s15
	s_lshl_b32 s8, s58, 7
	s_and_b32 s59, s8, 0x380
	s_mov_b64 s[8:9], s[30:31]
	v_mov_b32_e32 v0, v201
	s_add_u32 s14, s24, s14
	v_mbcnt_lo_u32_b32 v0, -1, v0
	v_mbcnt_hi_u32_b32 v0, -1, v0
	v_add_u32_e32 v202, s33, v0
	s_addc_u32 s15, s25, s15
	v_ashrrev_i32_e32 v44, 3, v202
	v_lshlrev_b32_e32 v0, 3, v202
	v_and_b32_e32 v45, 56, v0
	v_lshlrev_b32_e32 v0, 13, v44
	v_lshl_or_b32 v200, v45, 1, v0
	v_lshl_add_u64 v[12:13], s[14:15], 0, v[200:201]
	v_add_co_u32_e32 v32, vcc, s36, v12
	s_lshl_b32 s17, s59, 13
	s_nop 0
	v_addc_co_u32_e32 v33, vcc, 0, v13, vcc
	v_add_co_u32_e32 v34, vcc, s37, v12
	s_add_u32 s18, s20, s17
	s_nop 0
	v_addc_co_u32_e32 v35, vcc, 0, v13, vcc
	v_add_co_u32_e32 v36, vcc, s38, v12
	s_addc_u32 s19, s21, 0
	s_nop 0
	v_addc_co_u32_e32 v37, vcc, 0, v13, vcc
	v_lshl_add_u64 v[28:29], s[18:19], 0, v[200:201]
	v_add_co_u32_e32 v38, vcc, s36, v28
	global_load_dwordx4 v[0:3], v200, s[14:15]
	global_load_dwordx4 v[16:19], v200, s[18:19]
	v_addc_co_u32_e32 v39, vcc, 0, v29, vcc
	v_add_co_u32_e32 v40, vcc, s37, v28
	global_load_dwordx4 v[4:7], v[32:33], off
	global_load_dwordx4 v[8:11], v[34:35], off
	v_addc_co_u32_e32 v41, vcc, 0, v29, vcc
	v_add_co_u32_e32 v42, vcc, s38, v28
	global_load_dwordx4 v[12:15], v[36:37], off
	global_load_dwordx4 v[20:23], v[38:39], off
	v_addc_co_u32_e32 v43, vcc, 0, v29, vcc
	global_load_dwordx4 v[24:27], v[40:41], off
	global_load_dwordx4 v[28:31], v[42:43], off
	global_load_dwordx4 v[64:67], v200, s[14:15] offset:128
	global_load_dwordx4 v[68:71], v[32:33], off offset:128
	global_load_dwordx4 v[72:75], v[34:35], off offset:128
	global_load_dwordx4 v[76:79], v[36:37], off offset:128
	global_load_dwordx4 v[88:91], v200, s[18:19] offset:128
	global_load_dwordx4 v[96:99], v[38:39], off offset:128
	global_load_dwordx4 v[104:107], v[40:41], off offset:128
	global_load_dwordx4 v[108:111], v[42:43], off offset:128
	s_waitcnt lgkmcnt(0)
	s_barrier
	global_load_dwordx4 v[84:87], v[32:33], off offset:256
	global_load_dwordx4 v[92:95], v[34:35], off offset:256
	global_load_dwordx4 v[80:83], v200, s[14:15] offset:256
	global_load_dwordx4 v[112:115], v200, s[18:19] offset:256
	global_load_dwordx4 v[100:103], v[36:37], off offset:256
	global_load_dwordx4 v[116:119], v[38:39], off offset:256
	global_load_dwordx4 v[120:123], v[40:41], off offset:256
	global_load_dwordx4 v[124:127], v[42:43], off offset:256
	v_mul_lo_u32 v44, v44, s35
	v_add_lshl_u32 v206, v44, v45, 1
	v_and_b32_e32 v203, 31, v202
	v_bfe_u32 v204, v202, 5, 1
	s_mov_b32 s17, 0
	s_waitcnt vmcnt(0)
	ds_write_b128 v206, v[0:3]
	ds_write_b128 v206, v[4:7] offset:4608
	ds_write_b128 v206, v[8:11] offset:9216
	ds_write_b128 v206, v[12:15] offset:13824
	ds_write_b128 v206, v[16:19] offset:18432
	ds_write_b128 v206, v[20:23] offset:23040
	ds_write_b128 v206, v[24:27] offset:27648
	ds_write_b128 v206, v[28:31] offset:32256
	v_ashrrev_i32_e32 v0, 1, v202
	v_and_b32_e32 v205, 0xffffffc0, v0
	v_or_b32_e32 v0, v205, v203
	v_and_b32_e32 v2, 0x5f, v202
	v_lshlrev_b32_e32 v1, 4, v204
	v_mul_u32_u24_e32 v2, 0x90, v2
	v_mul_lo_u32 v3, v0, s39
	v_mov_b32_e32 v0, 0
	v_add_u32_e32 v207, v1, v3
	v_add_u32_e32 v208, v1, v2
	v_mov_b32_e32 v1, v0
	v_mov_b32_e32 v2, v0
	v_mov_b32_e32 v3, v0
	v_mov_b32_e32 v4, v0
	v_mov_b32_e32 v5, v0
	v_mov_b32_e32 v6, v0
	v_mov_b32_e32 v7, v0
	v_mov_b32_e32 v8, v0
	v_mov_b32_e32 v9, v0
	v_mov_b32_e32 v10, v0
	v_mov_b32_e32 v11, v0
	v_mov_b32_e32 v12, v0
	v_mov_b32_e32 v13, v0
	v_mov_b32_e32 v14, v0
	v_mov_b32_e32 v15, v0
	v_mov_b32_e32 v32, v0
	v_mov_b32_e32 v33, v0
	v_mov_b32_e32 v34, v0
	v_mov_b32_e32 v35, v0
	v_mov_b32_e32 v36, v0
	v_mov_b32_e32 v37, v0
	v_mov_b32_e32 v38, v0
	v_mov_b32_e32 v39, v0
	v_mov_b32_e32 v40, v0
	v_mov_b32_e32 v41, v0
	v_mov_b32_e32 v42, v0
	v_mov_b32_e32 v43, v0
	v_mov_b32_e32 v44, v0
	v_mov_b32_e32 v45, v0
	v_mov_b32_e32 v46, v0
	v_mov_b32_e32 v47, v0
	v_mov_b32_e32 v16, v0
	v_mov_b32_e32 v17, v0
	v_mov_b32_e32 v18, v0
	v_mov_b32_e32 v19, v0
	v_mov_b32_e32 v20, v0
	v_mov_b32_e32 v21, v0
	v_mov_b32_e32 v22, v0
	v_mov_b32_e32 v23, v0
	v_mov_b32_e32 v24, v0
	v_mov_b32_e32 v25, v0
	v_mov_b32_e32 v26, v0
	v_mov_b32_e32 v27, v0
	v_mov_b32_e32 v28, v0
	v_mov_b32_e32 v29, v0
	v_mov_b32_e32 v30, v0
	v_mov_b32_e32 v31, v0
	v_mov_b32_e32 v48, v0
	v_mov_b32_e32 v49, v0
	v_mov_b32_e32 v50, v0
	v_mov_b32_e32 v51, v0
	v_mov_b32_e32 v52, v0
	v_mov_b32_e32 v53, v0
	v_mov_b32_e32 v54, v0
	v_mov_b32_e32 v55, v0
	v_mov_b32_e32 v56, v0
	v_mov_b32_e32 v57, v0
	v_mov_b32_e32 v58, v0
	v_mov_b32_e32 v59, v0
	v_mov_b32_e32 v60, v0
	v_mov_b32_e32 v61, v0
	v_mov_b32_e32 v62, v0
	v_mov_b32_e32 v63, v0
	s_waitcnt lgkmcnt(0)
	s_barrier
	v_add_u32_e32 v209, 0x7157000, v200
	v_add_u32_e32 v210, 0x7197000, v200
	v_add_u32_e32 v211, 0x71d7000, v200
	v_add_u32_e32 v212, 0x7217000, v200
	v_add_u32_e32 v213, 0xec0000, v200
	v_add_u32_e32 v214, 0xf00000, v200
	v_add_u32_e32 v215, 0xf40000, v200
	v_add_u32_e32 v216, 0xf80000, v200
	s_branch .LBB0_2047

.LBB0_2047:
	ds_read_b128 v[176:179], v207
	ds_read_b128 v[144:147], v207 offset:32
	ds_read_b128 v[184:187], v208 offset:18432
	ds_read_b128 v[148:151], v208 offset:18464
	ds_read_b128 v[180:183], v207 offset:4608
	ds_read_b128 v[156:159], v207 offset:4640
	ds_read_b128 v[188:191], v208 offset:23040
	ds_read_b128 v[164:167], v208 offset:23072
	ds_read_b128 v[152:155], v207 offset:64
	ds_read_b128 v[128:131], v207 offset:96
	ds_read_b128 v[160:163], v207 offset:4672
	ds_read_b128 v[136:139], v207 offset:4704
	ds_read_b128 v[168:171], v208 offset:18496
	ds_read_b128 v[132:135], v208 offset:18528
	ds_read_b128 v[172:175], v208 offset:23104
	ds_read_b128 v[140:143], v208 offset:23136
	s_cmp_lt_u32 s17, 61
	s_waitcnt lgkmcnt(0)
	s_barrier
	s_waitcnt vmcnt(7)
	ds_write_b128 v206, v[64:67]
	s_waitcnt vmcnt(6)
	ds_write_b128 v206, v[68:71] offset:4608
	s_waitcnt vmcnt(5)
	ds_write_b128 v206, v[72:75] offset:9216
	s_waitcnt vmcnt(4)
	ds_write_b128 v206, v[76:79] offset:13824
	s_waitcnt vmcnt(3)
	ds_write_b128 v206, v[88:91] offset:18432
	s_waitcnt vmcnt(2)
	ds_write_b128 v206, v[96:99] offset:23040
	s_waitcnt vmcnt(1)
	ds_write_b128 v206, v[104:107] offset:27648
	s_waitcnt vmcnt(0)
	ds_write_b128 v206, v[108:111] offset:32256
	s_cbranch_scc0 .LBB0_2049
	global_load_dwordx4 v[64:67], v209, s[12:13] offset:2688
	global_load_dwordx4 v[68:71], v210, s[12:13] offset:2688
	global_load_dwordx4 v[72:75], v211, s[12:13] offset:2688
	global_load_dwordx4 v[76:79], v212, s[12:13] offset:2688
	global_load_dwordx4 v[88:91], v213, s[10:11] offset:384
	global_load_dwordx4 v[96:99], v214, s[10:11] offset:384
	global_load_dwordx4 v[104:107], v215, s[10:11] offset:384
	global_load_dwordx4 v[108:111], v216, s[10:11] offset:384
.LBB0_2049:
	v_mfma_f32_32x32x16_bf16 v[48:63], v[176:179], v[184:187], v[48:63]
	s_waitcnt lgkmcnt(0)
	s_barrier
	s_cmp_gt_u32 s17, 61
	s_cselect_b64 s[14:15], -1, 0
	s_and_b64 vcc, exec, s[14:15]
	v_mfma_f32_32x32x16_bf16 v[16:31], v[176:179], v[188:191], v[16:31]
	v_mfma_f32_32x32x16_bf16 v[32:47], v[180:183], v[184:187], v[32:47]
	v_mfma_f32_32x32x16_bf16 v[0:15], v[180:183], v[188:191], v[0:15]
	v_mfma_f32_32x32x16_bf16 v[48:63], v[144:147], v[148:151], v[48:63]
	v_mfma_f32_32x32x16_bf16 v[16:31], v[144:147], v[164:167], v[16:31]
	v_mfma_f32_32x32x16_bf16 v[32:47], v[156:159], v[148:151], v[32:47]
	v_mfma_f32_32x32x16_bf16 v[0:15], v[156:159], v[164:167], v[0:15]
	v_mfma_f32_32x32x16_bf16 v[48:63], v[152:155], v[168:171], v[48:63]
	v_mfma_f32_32x32x16_bf16 v[16:31], v[152:155], v[172:175], v[16:31]
	v_mfma_f32_32x32x16_bf16 v[32:47], v[160:163], v[168:171], v[32:47]
	v_mfma_f32_32x32x16_bf16 v[0:15], v[160:163], v[172:175], v[0:15]
	ds_read_b128 v[176:179], v207
	ds_read_b128 v[152:155], v207 offset:32
	ds_read_b128 v[188:191], v208 offset:18432
	ds_read_b128 v[156:159], v208 offset:18464
	ds_read_b128 v[184:187], v207 offset:4608
	ds_read_b128 v[160:163], v207 offset:4640
	v_mfma_f32_32x32x16_bf16 v[48:63], v[128:131], v[132:135], v[48:63]
	v_mfma_f32_32x32x16_bf16 v[16:31], v[128:131], v[140:143], v[16:31]
	ds_read_b128 v[196:199], v208 offset:23040
	ds_read_b128 v[172:175], v208 offset:23072
	ds_read_b128 v[164:167], v207 offset:64
	ds_read_b128 v[148:151], v207 offset:96
	ds_read_b128 v[168:171], v207 offset:4672
	ds_read_b128 v[128:131], v207 offset:4704
	ds_read_b128 v[180:183], v208 offset:18496
	ds_read_b128 v[144:147], v208 offset:18528
	v_mfma_f32_32x32x16_bf16 v[32:47], v[136:139], v[132:135], v[32:47]
	ds_read_b128 v[192:195], v208 offset:23104
	ds_read_b128 v[132:135], v208 offset:23136
	s_waitcnt lgkmcnt(0)
	s_barrier
	v_mfma_f32_32x32x16_bf16 v[0:15], v[136:139], v[140:143], v[0:15]
	s_cbranch_vccnz .LBB0_2046
	s_cmp_gt_u32 s17, 59
	ds_write_b128 v206, v[80:83]
	ds_write_b128 v206, v[84:87] offset:4608
	ds_write_b128 v206, v[92:95] offset:9216
	ds_write_b128 v206, v[100:103] offset:13824
	ds_write_b128 v206, v[112:115] offset:18432
	ds_write_b128 v206, v[116:119] offset:23040
	ds_write_b128 v206, v[120:123] offset:27648
	ds_write_b128 v206, v[124:127] offset:32256
	s_cbranch_scc1 .LBB0_2046
	global_load_dwordx4 v[80:83], v209, s[12:13] offset:2816
	global_load_dwordx4 v[84:87], v210, s[12:13] offset:2816
	global_load_dwordx4 v[92:95], v211, s[12:13] offset:2816
	global_load_dwordx4 v[100:103], v212, s[12:13] offset:2816
	global_load_dwordx4 v[112:115], v213, s[10:11] offset:512
	global_load_dwordx4 v[116:119], v214, s[10:11] offset:512
	global_load_dwordx4 v[120:123], v215, s[10:11] offset:512
	global_load_dwordx4 v[124:127], v216, s[10:11] offset:512
	s_branch .LBB0_2046
